# grid barrier rewritten: per-XCD flag lines polled through L2, leaders publish write-through generation words, L1 invalidate issued early
# speedup vs baseline: 1.0747x; 1.0099x over previous
_Z14fwd_megakernel6Params:
	s_load_dwordx4 s[92:95], s[0:1], 0x140
	s_load_dword s64, s[0:1], 0x150
	s_add_u32 s4, s0, 0x148
	s_addc_u32 s5, s1, 0
	s_getreg_b32 s3, hwreg(HW_REG_XCC_ID, 0, 4)
	s_waitcnt lgkmcnt(0)
	s_add_u32 s14, s92, 0xb500900
	v_and_b32_e32 v166, 0x3ff, v0
	s_addc_u32 s15, s93, 0
	s_and_b32 s3, s3, 15
	v_cmp_eq_u32_e64 s[74:75], 0, v166
	s_and_saveexec_b64 s[6:7], s[74:75]
	s_cbranch_execz .LBB0_3
	s_mov_b64 s[8:9], exec
	v_mbcnt_lo_u32_b32 v1, s8, 0
	v_mbcnt_hi_u32_b32 v1, s9, v1
	v_cmp_eq_u32_e32 vcc, 0, v1
	s_and_b64 s[10:11], exec, vcc
	s_mov_b64 exec, s[10:11]
	s_cbranch_execz .LBB0_3
	s_lshl_b32 s10, s3, 8
	s_bcnt1_i32_b64 s8, s[8:9]
	v_mov_b32_e32 v1, s10
	v_mov_b32_e32 v2, s8
	global_atomic_add v2, v1, v2, s[14:15] offset:1024 sc0
	s_waitcnt vmcnt(0)
	v_readfirstlane_b32 s8, v2
	s_nop 1
	v_writelane_b32 v240, s8, 62
.LBB0_3:
	s_or_b64 exec, exec, s[6:7]
	v_writelane_b32 v240, s3, 61
	v_writelane_b32 v240, 0, 63
	v_writelane_b32 v240, 0, 60
	v_writelane_b32 v240, 0, 59
	s_load_dwordx16 s[16:31], s[0:1], 0x0
	v_mov_b32_e32 v2, v166
	s_cmp_lg_u32 s2, 0
	s_waitcnt lgkmcnt(0)
	v_writelane_b32 v245, s16, 0
	s_nop 1
	v_writelane_b32 v245, s17, 1
	v_writelane_b32 v245, s18, 2
	v_writelane_b32 v245, s19, 3
	v_writelane_b32 v245, s20, 4
	v_writelane_b32 v245, s21, 5
	v_writelane_b32 v245, s22, 6
	v_writelane_b32 v245, s23, 7
	v_writelane_b32 v245, s24, 8
	v_writelane_b32 v245, s25, 9
	v_writelane_b32 v245, s26, 10
	v_writelane_b32 v245, s27, 11
	v_writelane_b32 v245, s28, 12
	v_writelane_b32 v245, s29, 13
	v_writelane_b32 v245, s30, 14
	v_writelane_b32 v245, s31, 15
	s_cbranch_scc1 .LBB0_9
	v_ashrrev_i32_e32 v3, 31, v2
	v_lshl_add_u64 v[4:5], v[2:3], 2, s[92:93]
	v_add_co_u32_e32 v8, vcc, 0xb500000, v4
	v_mov_b32_e32 v6, 0
	s_nop 0
	v_addc_co_u32_e32 v9, vcc, 0, v5, vcc
	v_cmp_gt_i32_e32 vcc, 2, v2
	global_store_dword v[8:9], v6, off offset:256
	s_and_saveexec_b64 s[6:7], vcc
	s_cbranch_execz .LBB0_8
	s_load_dwordx16 s[16:31], s[0:1], 0x0
	v_lshlrev_b32_e32 v10, 8, v2
	v_ashrrev_i32_e32 v11, 31, v10
	s_mov_b64 s[8:9], 0
	v_mov_b32_e32 v7, v6
	s_waitcnt lgkmcnt(0)
	v_mov_b32_e32 v8, s26
	v_mov_b32_e32 v9, s27
	v_lshl_add_u64 v[8:9], v[10:11], 2, v[8:9]

.LBB0_130:
	s_waitcnt vmcnt(0)
	s_waitcnt vmcnt(0)
	s_barrier
	s_and_saveexec_b64 s[0:1], s[74:75]
	s_cbranch_execz .LBB0_183
	s_waitcnt vmcnt(0) lgkmcnt(0)
	v_readlane_b32 s21, v240, 63
	v_readlane_b32 s26, v240, 61
	v_readlane_b32 s27, v240, 62
	s_add_u32 s24, s92, 0xb500900
	s_addc_u32 s25, s93, 0
	s_add_i32 s21, s21, 1
	s_nop 1
	v_writelane_b32 v240, s21, 63
	v_mov_b32_e32 v0, s26
	v_lshlrev_b32_e32 v0, 7, v0
	v_lshl_add_u32 v0, s27, 2, v0
	v_add_u32_e32 v0, 0x1400, v0
	v_mov_b32_e32 v1, s21
	global_store_dword v0, v1, s[24:25]
	s_cmp_lg_u32 s27, 0
	s_cbranch_scc1 .Lnc0_f
	buffer_inv sc1
	v_readlane_b32 s28, v240, 60
	s_mov_b32 exec_lo, -1
	s_mov_b32 exec_hi, 0
	v_mbcnt_lo_u32_b32 v2, -1, 0
	s_cmp_lg_u32 s28, 0
	s_cbranch_scc1 .Lnc0_have
	v_lshlrev_b32_e32 v3, 8, v2
	v_add_u32_e32 v3, 0x400, v3
	global_load_dword v4, v3, s[24:25] sc0 sc1
	s_waitcnt vmcnt(0)
	v_readlane_b32 s28, v4, s26
	v_cmp_ne_u32_e32 vcc, 0, v4
	s_nop 3
	s_and_b32 s27, vcc_lo, 0xffff
	v_writelane_b32 v240, s28, 60
	v_writelane_b32 v240, s27, 59
.Lnc0_have:
	v_readlane_b32 s27, v240, 59
	v_lshlrev_b32_e32 v3, 2, v2
	v_lshl_add_u32 v3, s26, 7, v3
	v_add_u32_e32 v3, 0x1400, v3
	v_cmp_le_u32_e32 vcc, s28, v2
	s_nop 1
	v_cndmask_b32_e64 v8, 0, -1, vcc
.Lnc0_p1:
	global_load_dword v4, v3, s[24:25] sc1
	s_waitcnt vmcnt(0)
	v_or_b32_e32 v4, v4, v8
	v_cmp_gt_u32_e32 vcc, s21, v4
	s_cbranch_vccz .Lnc0_ok1
	s_nop 3
	s_branch .Lnc0_p1
.Lnc0_ok1:
	buffer_wbl2 sc1
	s_waitcnt vmcnt(0)
	s_mov_b64 exec, 1
	v_mov_b32_e32 v0, s26
	v_lshlrev_b32_e32 v0, 2, v0
	v_add_u32_e32 v0, 0x3400, v0
	global_store_dword v0, v1, s[24:25] sc0 sc1
	s_mov_b64 exec, 0xffff
	v_lshlrev_b32_e32 v3, 2, v2
	v_add_u32_e32 v3, 0x3400, v3
	v_lshrrev_b32_e64 v9, v2, s27
	v_and_b32_e32 v9, 1, v9
	v_add_u32_e32 v9, -1, v9
.Lnc0_p2:
	global_load_dword v4, v3, s[24:25] sc0 sc1
	s_waitcnt vmcnt(0)
	v_or_b32_e32 v4, v4, v9
	v_cmp_gt_u32_e32 vcc, s21, v4
	s_cbranch_vccz .Lnc0_ok2
	s_sleep 1
	s_branch .Lnc0_p2
.Lnc0_ok2:
	s_mov_b64 exec, 1
	v_mov_b32_e32 v0, s26
	v_lshlrev_b32_e32 v0, 8, v0
	v_add_u32_e32 v0, 0x2400, v0
	global_store_dword v0, v1, s[24:25]
	s_branch .Lnc0_done
.Lnc0_f:
	buffer_inv sc1
	v_mov_b32_e32 v0, s26
	v_lshlrev_b32_e32 v0, 8, v0
	v_add_u32_e32 v0, 0x2400, v0
.Lnc0_p3:
	global_load_dword v3, v0, s[24:25] sc1
	s_waitcnt vmcnt(0)
	v_cmp_gt_u32_e32 vcc, s21, v3
	s_cbranch_vccz .Lnc0_okf
	s_sleep 1
	s_branch .Lnc0_p3
.Lnc0_okf:
.Lnc0_done:
.LBB0_183:
	s_or_b64 exec, exec, s[0:1]
	s_xor_b64 s[0:1], s[60:61], -1
	s_mov_b32 s24, s46
	v_readlane_b32 s44, v245, 0
	v_writelane_b32 v241, s0, 20
	v_readlane_b32 s64, v245, 48
	v_readlane_b32 s45, v245, 1
	v_writelane_b32 v241, s1, 21
	s_and_b64 s[0:1], s[60:61], exec
	v_readlane_b32 s78, v245, 62
	v_readlane_b32 s79, v245, 63
	s_mov_b64 s[40:41], s[44:45]
	s_cselect_b32 s1, s41, s79
	s_cselect_b32 s0, s40, s78
	v_readlane_b32 s76, v245, 60
	v_readlane_b32 s46, v245, 2
	v_readlane_b32 s47, v245, 3
	v_readlane_b32 s50, v245, 6
	v_readlane_b32 s51, v245, 7
	v_writelane_b32 v241, s0, 22
	s_lshl_b32 s84, s24, 10
	s_mov_b64 s[46:47], s[50:51]
	v_writelane_b32 v241, s1, 23
	s_mov_b32 s76, s24
	s_lshl_b64 s[24:25], s[84:85], 2
	s_add_u32 s0, s46, s24
	v_writelane_b32 v241, s24, 24
	s_addc_u32 s1, s47, s25
	v_mov_b32_e32 v0, v166
	v_writelane_b32 v241, s25, 25
	v_writelane_b32 v241, s0, 26
	s_barrier
	s_nop 0
	v_writelane_b32 v241, s1, 27
	v_readlane_b32 s0, v244, 3
	v_ashrrev_i32_e32 v1, 6, v0
	v_readlane_b32 s65, v245, 49
	v_add_u32_e32 v16, s0, v1
	s_mov_b32 s0, 0x10000
	v_cmp_gt_i32_e32 vcc, s0, v16
	v_readlane_b32 s66, v245, 50
	v_readlane_b32 s67, v245, 51
	v_readlane_b32 s68, v245, 52
	v_readlane_b32 s69, v245, 53
	v_readlane_b32 s70, v245, 54
	v_readlane_b32 s71, v245, 55
	v_readlane_b32 s72, v245, 56
	v_readlane_b32 s73, v245, 57
	v_readlane_b32 s74, v245, 58
	v_readlane_b32 s75, v245, 59
	v_readlane_b32 s77, v245, 61
	v_readlane_b32 s48, v245, 4
	v_readlane_b32 s49, v245, 5
	v_readlane_b32 s52, v245, 8
	v_readlane_b32 s53, v245, 9
	v_readlane_b32 s54, v245, 10
	v_readlane_b32 s55, v245, 11
	v_readlane_b32 s56, v245, 12
	v_readlane_b32 s57, v245, 13
	v_readlane_b32 s58, v245, 14
	v_readlane_b32 s59, v245, 15
	s_and_saveexec_b64 s[24:25], vcc
	s_cbranch_execz .LBB0_186
	v_and_b32_e32 v17, 63, v0
	v_readlane_b32 s0, v241, 26
	v_lshlrev_b32_e32 v64, 4, v17
	v_readlane_b32 s1, v241, 27
	s_nop 4
	global_load_dwordx4 v[0:3], v64, s[0:1]
	global_load_dwordx4 v[4:7], v64, s[0:1] offset:1024
	global_load_dwordx4 v[8:11], v64, s[0:1] offset:2048
	global_load_dwordx4 v[12:15], v64, s[0:1] offset:3072
	v_cmp_lt_i32_e32 vcc, v157, v168
	v_lshlrev_b32_e32 v20, 2, v17
	v_readlane_b32 s0, v241, 22
	v_cndmask_b32_e32 v18, v155, v157, vcc
	v_cmp_lt_i32_e32 vcc, v169, v168
	v_lshlrev_b32_e32 v26, 2, v18
	v_or_b32_e32 v22, 0x100, v20
	v_cndmask_b32_e32 v18, v155, v169, vcc
	v_or_b32_e32 v24, 0x200, v20
	v_or_b32_e32 v28, 0x300, v20
	v_readlane_b32 s1, v241, 23
	v_lshlrev_b32_e32 v27, 2, v18
	s_mov_b64 s[28:29], 0
	v_lshl_add_u64 v[18:19], s[0:1], 0, v[64:65]
	v_lshlrev_b32_e32 v64, 1, v20
	v_lshlrev_b32_e32 v20, 1, v22
	v_mov_b32_e32 v21, v65
	v_lshlrev_b32_e32 v22, 1, v24
	v_mov_b32_e32 v23, v65
	v_lshlrev_b32_e32 v24, 1, v28
	v_mov_b32_e32 v25, v65

.LBB0_186:
	s_or_b64 exec, exec, s[24:25]
	s_waitcnt vmcnt(0)
	v_readlane_b32 s46, v241, 17
	v_readlane_b32 s48, v243, 15
	v_readlane_b32 s64, v243, 25
	v_readlane_b32 s66, v243, 27
	v_readlane_b32 s70, v243, 29
	v_readlane_b32 s72, v243, 31
	v_readlane_b32 s74, v243, 35
	v_readlane_b32 s47, v241, 18
	v_readlane_b32 s49, v243, 16
	v_readlane_b32 s50, v243, 17
	v_readlane_b32 s51, v243, 18
	v_readlane_b32 s65, v243, 26
	v_readlane_b32 s67, v243, 28
	v_readlane_b32 s71, v243, 30
	v_readlane_b32 s73, v243, 32
	v_readlane_b32 s75, v243, 36
	s_barrier
	s_and_saveexec_b64 s[0:1], s[46:47]
	v_readlane_b32 s2, v241, 19
	s_mov_b32 s69, 0x5040100
	s_cbranch_execz .LBB0_239
	s_waitcnt vmcnt(0) lgkmcnt(0)
	v_readlane_b32 s21, v240, 63
	v_readlane_b32 s26, v240, 61
	v_readlane_b32 s27, v240, 62
	s_add_u32 s24, s92, 0xb500900
	s_addc_u32 s25, s93, 0
	s_add_i32 s21, s21, 1
	s_nop 1
	v_writelane_b32 v240, s21, 63
	v_mov_b32_e32 v0, s26
	v_lshlrev_b32_e32 v0, 7, v0
	v_lshl_add_u32 v0, s27, 2, v0
	v_add_u32_e32 v0, 0x1400, v0
	v_mov_b32_e32 v1, s21
	global_store_dword v0, v1, s[24:25]
	s_cmp_lg_u32 s27, 0
	s_cbranch_scc1 .Lnc1_f
	buffer_inv sc1
	v_readlane_b32 s28, v240, 60
	s_mov_b32 exec_lo, -1
	s_mov_b32 exec_hi, 0
	v_mbcnt_lo_u32_b32 v2, -1, 0
	s_cmp_lg_u32 s28, 0
	s_cbranch_scc1 .Lnc1_have
	v_lshlrev_b32_e32 v3, 8, v2
	v_add_u32_e32 v3, 0x400, v3
	global_load_dword v4, v3, s[24:25] sc0 sc1
	s_waitcnt vmcnt(0)
	v_readlane_b32 s28, v4, s26
	v_cmp_ne_u32_e32 vcc, 0, v4
	s_nop 3
	s_and_b32 s27, vcc_lo, 0xffff
	v_writelane_b32 v240, s28, 60
	v_writelane_b32 v240, s27, 59

.Lnc1_okf:
.Lnc1_done:
.LBB0_239:
	v_writelane_b32 v241, s60, 28
	s_nop 1
	v_writelane_b32 v241, s61, 29
	s_or_b64 exec, exec, s[0:1]
	v_readlane_b32 s0, v243, 21
	v_readlane_b32 s1, v243, 22
	s_andn2_b64 vcc, exec, s[0:1]
	s_mul_i32 s61, s76, 0x1380000
	s_barrier
	s_cbranch_vccnz .LBB0_271
	v_mov_b32_e32 v0, v166
	s_barrier
	s_add_u32 s0, s92, s61
	v_lshlrev_b32_e32 v2, 4, v0
	v_and_b32_e32 v3, 32, v0
	v_ashrrev_i32_e32 v1, 6, v0
	v_bitop3_b32 v2, v2, v3, 48 bitop3:0x6c
	v_lshlrev_b32_e32 v0, 8, v0
	s_addc_u32 s1, s93, 0
	v_lshrrev_b32_e32 v2, 1, v2
	v_and_b32_e32 v0, 0x3c00, v0
	v_lshlrev_b32_e32 v3, 14, v1
	s_add_u32 s21, s0, 0x980000
	v_or3_b32 v64, v3, v0, v2
	v_lshlrev_b32_e32 v10, 10, v1
	v_readlane_b32 s26, v242, 20
	s_addc_u32 s40, s1, 0
	v_readlane_b32 s0, v242, 22
	v_add_u32_e32 v0, 0x20000, v64
	v_mov_b32_e32 v1, v65
	v_lshlrev_b64 v[2:3], 1, v[64:65]
	v_readlane_b32 s27, v242, 21
	v_readfirstlane_b32 s24, v10
	v_add_u32_e32 v8, 0x2000, v10
	v_readlane_b32 s1, v242, 23
	s_add_u32 s0, s21, s0
	v_lshl_add_u64 v[4:5], s[26:27], 0, v[2:3]
	s_mov_b32 m0, s24
	v_lshlrev_b64 v[0:1], 1, v[0:1]
	v_readfirstlane_b32 s24, v8
	v_add_u32_e32 v8, 0x4000, v10
	s_addc_u32 s1, s40, s1
	global_load_lds_dwordx4 v[4:5], off
	v_lshl_add_u64 v[6:7], s[26:27], 0, v[0:1]
	s_mov_b32 m0, s24
	v_readfirstlane_b32 s24, v8
	v_add_u32_e32 v8, 0x6000, v10
	global_load_lds_dwordx4 v[6:7], off
	v_lshl_add_u64 v[2:3], s[0:1], 0, v[2:3]
	s_mov_b32 m0, s24
	v_lshl_add_u64 v[0:1], s[0:1], 0, v[0:1]
	v_readfirstlane_b32 s0, v8
	v_add_u32_e32 v11, 0x8000, v10
	global_load_lds_dwordx4 v[2:3], off
	s_mov_b32 m0, s0
	v_readfirstlane_b32 s0, v11
	v_add_u32_e32 v11, 0xa000, v10
	global_load_lds_dwordx4 v[0:1], off
	v_lshl_add_u64 v[8:9], v[4:5], 0, 64
	s_mov_b32 m0, s0
	v_readfirstlane_b32 s0, v11
	v_add_u32_e32 v11, 0xc000, v10
	global_load_lds_dwordx4 v[8:9], off
	v_lshl_add_u64 v[8:9], v[6:7], 0, 64
	s_mov_b32 m0, s0
	v_readfirstlane_b32 s0, v11
	v_add_u32_e32 v11, 0xe000, v10
	global_load_lds_dwordx4 v[8:9], off
	v_lshl_add_u64 v[8:9], v[2:3], 0, 64
	s_mov_b32 m0, s0
	v_readfirstlane_b32 s0, v11
	v_add_u32_e32 v11, 0x10000, v10
	global_load_lds_dwordx4 v[8:9], off
	v_lshl_add_u64 v[8:9], v[0:1], 0, 64
	s_mov_b32 m0, s0
	v_readfirstlane_b32 s0, v11
	v_add_u32_e32 v11, 0x12000, v10
	global_load_lds_dwordx4 v[8:9], off
	v_lshl_add_u64 v[8:9], v[4:5], 0, s[34:35]
	s_mov_b32 m0, s0
	v_readfirstlane_b32 s0, v11
	v_add_u32_e32 v11, 0x14000, v10
	global_load_lds_dwordx4 v[8:9], off
	v_lshl_add_u64 v[8:9], v[6:7], 0, s[34:35]
	s_mov_b32 m0, s0
	v_readfirstlane_b32 s0, v11
	v_add_u32_e32 v11, 0x16000, v10
	global_load_lds_dwordx4 v[8:9], off
	v_lshl_add_u64 v[8:9], v[2:3], 0, s[34:35]
	s_mov_b32 m0, s0
	v_readfirstlane_b32 s0, v11
	global_load_lds_dwordx4 v[8:9], off
	v_lshl_add_u64 v[8:9], v[0:1], 0, s[34:35]
	s_mov_b32 m0, s0
	v_lshl_add_u64 v[4:5], v[4:5], 0, s[82:83]
	global_load_lds_dwordx4 v[8:9], off
	v_add_u32_e32 v8, 0x18000, v10
	v_lshl_add_u64 v[2:3], v[2:3], 0, s[82:83]
	v_readfirstlane_b32 s0, v8
	s_mov_b32 m0, s0
	v_lshl_add_u64 v[0:1], v[0:1], 0, s[82:83]
	global_load_lds_dwordx4 v[4:5], off
	v_lshl_add_u64 v[4:5], v[6:7], 0, s[82:83]
	v_add_u32_e32 v6, 0x1a000, v10
	s_mov_b32 s41, 1
	v_readfirstlane_b32 s0, v6
	s_mov_b32 m0, s0
	s_mov_b32 s60, 0
	global_load_lds_dwordx4 v[4:5], off
	v_add_u32_e32 v4, 0x1c000, v10
	v_readlane_b32 s36, v242, 43
	v_readfirstlane_b32 s0, v4
	s_mov_b32 m0, s0
	v_readlane_b32 s26, v242, 53
	global_load_lds_dwordx4 v[2:3], off
	v_add_u32_e32 v2, 0x1e000, v10
	v_readlane_b32 s37, v242, 44
	v_readfirstlane_b32 s0, v2
	s_mov_b32 m0, s0
	v_readlane_b32 s0, v242, 55
	global_load_lds_dwordx4 v[0:1], off
	s_add_u32 s44, s0, s61
	v_readlane_b32 s0, v242, 56
	s_addc_u32 s45, s0, 0
	v_readlane_b32 s27, v242, 54
	s_branch .LBB0_242

.LBB0_271:
	s_waitcnt vmcnt(0)
	s_waitcnt vmcnt(0) lgkmcnt(0)
	s_barrier
	s_and_saveexec_b64 s[0:1], s[46:47]
	s_cbranch_execz .LBB0_324
	s_waitcnt vmcnt(0) lgkmcnt(0)
	v_readlane_b32 s21, v240, 63
	v_readlane_b32 s26, v240, 61
	v_readlane_b32 s27, v240, 62
	s_add_u32 s24, s92, 0xb500900
	s_addc_u32 s25, s93, 0
	s_add_i32 s21, s21, 1
	s_nop 1
	v_writelane_b32 v240, s21, 63
	v_mov_b32_e32 v0, s26
	v_lshlrev_b32_e32 v0, 7, v0
	v_lshl_add_u32 v0, s27, 2, v0
	v_add_u32_e32 v0, 0x1400, v0
	v_mov_b32_e32 v1, s21
	global_store_dword v0, v1, s[24:25]
	s_cmp_lg_u32 s27, 0
	s_cbranch_scc1 .Lnc2_f
	buffer_inv sc1
	v_readlane_b32 s28, v240, 60
	s_mov_b32 exec_lo, -1
	s_mov_b32 exec_hi, 0
	v_mbcnt_lo_u32_b32 v2, -1, 0
	s_cmp_lg_u32 s28, 0
	s_cbranch_scc1 .Lnc2_have
	v_lshlrev_b32_e32 v3, 8, v2
	v_add_u32_e32 v3, 0x400, v3
	global_load_dword v4, v3, s[24:25] sc0 sc1
	s_waitcnt vmcnt(0)
	v_readlane_b32 s28, v4, s26
	v_cmp_ne_u32_e32 vcc, 0, v4
	s_nop 3
	s_and_b32 s27, vcc_lo, 0xffff
	v_writelane_b32 v240, s28, 60
	v_writelane_b32 v240, s27, 59

.Lnc2_okf:
.Lnc2_done:
.LBB0_324:
	s_or_b64 exec, exec, s[0:1]
	v_readlane_b32 s0, v243, 23
	v_readlane_b32 s1, v243, 24
	s_andn2_b64 vcc, exec, s[0:1]
	s_mov_b64 s[0:1], -1
	s_barrier
	s_cbranch_vccnz .LBB0_326
	s_lshl_b32 s68, s76, 8
	s_mov_b64 s[0:1], 0

.LBB0_503:
	s_waitcnt vmcnt(0)
	s_waitcnt lgkmcnt(0)
	s_barrier
	s_and_saveexec_b64 s[0:1], s[74:75]
	s_branch .LBB0_556
	s_waitcnt vmcnt(0) lgkmcnt(0)
	v_readlane_b32 s26, v240, 63
	v_readlane_b32 s27, v240, 61
	v_readlane_b32 s28, v240, 62
	s_add_u32 s24, s92, 0xb500900
	s_addc_u32 s25, s93, 0
	s_add_i32 s26, s26, 1
	s_nop 1
	v_writelane_b32 v240, s26, 63
	v_mov_b32_e32 v0, s27
	v_lshlrev_b32_e32 v0, 7, v0
	v_lshl_add_u32 v0, s28, 2, v0
	v_add_u32_e32 v0, 0x1400, v0
	v_mov_b32_e32 v1, s26
	global_store_dword v0, v1, s[24:25]
	s_cmp_lg_u32 s28, 0
	s_cbranch_scc1 .Lnc3_f
	buffer_inv sc1
	v_readlane_b32 s29, v240, 60
	s_mov_b32 exec_lo, -1
	s_mov_b32 exec_hi, 0
	v_mbcnt_lo_u32_b32 v2, -1, 0
	s_cmp_lg_u32 s29, 0
	s_cbranch_scc1 .Lnc3_have
	v_lshlrev_b32_e32 v3, 8, v2
	v_add_u32_e32 v3, 0x400, v3
	global_load_dword v4, v3, s[24:25] sc0 sc1
	s_waitcnt vmcnt(0)
	v_readlane_b32 s29, v4, s27
	v_cmp_ne_u32_e32 vcc, 0, v4
	s_nop 3
	s_and_b32 s28, vcc_lo, 0xffff
	v_writelane_b32 v240, s29, 60
	v_writelane_b32 v240, s28, 59
.Lnc3_have:
	v_readlane_b32 s28, v240, 59
	v_lshlrev_b32_e32 v3, 2, v2
	v_lshl_add_u32 v3, s27, 7, v3
	v_add_u32_e32 v3, 0x1400, v3
	v_cmp_le_u32_e32 vcc, s29, v2
	s_nop 1
	v_cndmask_b32_e64 v8, 0, -1, vcc
.Lnc3_p1:
	global_load_dword v4, v3, s[24:25] sc1
	s_waitcnt vmcnt(0)
	v_or_b32_e32 v4, v4, v8
	v_cmp_gt_u32_e32 vcc, s26, v4
	s_cbranch_vccz .Lnc3_ok1
	s_nop 3
	s_branch .Lnc3_p1
.Lnc3_ok1:
	buffer_wbl2 sc1
	s_waitcnt vmcnt(0)
	s_mov_b64 exec, 1
	v_mov_b32_e32 v0, s27
	v_lshlrev_b32_e32 v0, 2, v0
	v_add_u32_e32 v0, 0x3400, v0
	global_store_dword v0, v1, s[24:25] sc0 sc1
	s_mov_b64 exec, 0xffff
	v_lshlrev_b32_e32 v3, 2, v2
	v_add_u32_e32 v3, 0x3400, v3
	v_lshrrev_b32_e64 v9, v2, s28
	v_and_b32_e32 v9, 1, v9
	v_add_u32_e32 v9, -1, v9
.Lnc3_p2:
	global_load_dword v4, v3, s[24:25] sc0 sc1
	s_waitcnt vmcnt(0)
	v_or_b32_e32 v4, v4, v9
	v_cmp_gt_u32_e32 vcc, s26, v4
	s_cbranch_vccz .Lnc3_ok2
	s_sleep 1
	s_branch .Lnc3_p2
.Lnc3_ok2:
	s_mov_b64 exec, 1
	v_mov_b32_e32 v0, s27
	v_lshlrev_b32_e32 v0, 8, v0
	v_add_u32_e32 v0, 0x2400, v0
	global_store_dword v0, v1, s[24:25]
	s_branch .Lnc3_done
.Lnc3_f:
	buffer_inv sc1
	v_mov_b32_e32 v0, s27
	v_lshlrev_b32_e32 v0, 8, v0
	v_add_u32_e32 v0, 0x2400, v0
.Lnc3_p3:
	global_load_dword v3, v0, s[24:25] sc1
	s_waitcnt vmcnt(0)
	v_cmp_gt_u32_e32 vcc, s26, v3
	s_cbranch_vccz .Lnc3_okf
	s_sleep 1
	s_branch .Lnc3_p3
.Lnc3_okf:
.Lnc3_done:
.LBB0_556:
	s_or_b64 exec, exec, s[0:1]
	v_readlane_b32 s0, v240, 27
	v_readlane_b32 s1, v240, 28
	s_lshl_b32 s84, s0, 24
	s_lshl_b64 s[24:25], s[84:85], 2
	v_readlane_b32 s0, v241, 22
	v_mov_b32_e32 v0, v166
	s_add_u32 s40, s0, s24
	s_barrier
	v_readlane_b32 s0, v244, 3
	v_ashrrev_i32_e32 v1, 6, v0
	v_readlane_b32 s1, v241, 23
	v_add_u32_e32 v24, s0, v1
	s_movk_i32 s0, 0x4000
	v_writelane_b32 v240, s24, 29
	s_addc_u32 s41, s1, s25
	v_cmp_gt_i32_e32 vcc, s0, v24
	v_writelane_b32 v240, s25, 30
	s_and_saveexec_b64 s[24:25], vcc
	s_cbranch_execz .LBB0_559
	v_and_b32_e32 v16, 63, v0
	v_readlane_b32 s0, v241, 26
	v_lshlrev_b32_e32 v64, 4, v16
	v_readlane_b32 s1, v241, 27
	s_nop 4
	global_load_dwordx4 v[0:3], v64, s[0:1]
	global_load_dwordx4 v[4:7], v64, s[0:1] offset:1024
	global_load_dwordx4 v[8:11], v64, s[0:1] offset:2048
	global_load_dwordx4 v[12:15], v64, s[0:1] offset:3072
	v_mbcnt_hi_u32_b32 v17, -1, v167
	v_and_b32_e32 v19, 64, v17
	v_xor_b32_e32 v18, 16, v17
	v_add_u32_e32 v19, 64, v19
	v_cmp_lt_i32_e32 vcc, v18, v19
	v_lshlrev_b32_e32 v16, 2, v16
	v_or_b32_e32 v20, 0x200, v16
	v_cndmask_b32_e32 v18, v17, v18, vcc
	v_lshlrev_b32_e32 v37, 2, v18
	v_xor_b32_e32 v18, 32, v17
	v_cmp_lt_i32_e32 vcc, v18, v19
	v_or_b32_e32 v22, 0x300, v16
	v_lshl_add_u64 v[26:27], s[40:41], 0, v[64:65]
	v_cndmask_b32_e32 v17, v17, v18, vcc
	v_or_b32_e32 v18, 0x100, v16
	v_lshlrev_b32_e32 v38, 2, v17
	s_mov_b64 s[28:29], 0
	v_lshlrev_b32_e32 v64, 1, v16
	v_lshlrev_b32_e32 v28, 1, v18
	v_lshlrev_b32_e32 v30, 1, v20
	v_lshlrev_b32_e32 v32, 1, v22

.LBB0_559:
	s_or_b64 exec, exec, s[24:25]
	s_waitcnt vmcnt(0)
	s_barrier
	s_and_saveexec_b64 s[0:1], s[74:75]
	v_readlane_b32 s2, v241, 19
	s_cbranch_execz .LBB0_612
	s_waitcnt vmcnt(0) lgkmcnt(0)
	v_readlane_b32 s26, v240, 63
	v_readlane_b32 s27, v240, 61
	v_readlane_b32 s28, v240, 62
	s_add_u32 s24, s92, 0xb500900
	s_addc_u32 s25, s93, 0
	s_add_i32 s26, s26, 1
	s_nop 1
	v_writelane_b32 v240, s26, 63
	v_mov_b32_e32 v0, s27
	v_lshlrev_b32_e32 v0, 7, v0
	v_lshl_add_u32 v0, s28, 2, v0
	v_add_u32_e32 v0, 0x1400, v0
	v_mov_b32_e32 v1, s26
	global_store_dword v0, v1, s[24:25]
	s_cmp_lg_u32 s28, 0
	s_cbranch_scc1 .Lnc4_f
	buffer_inv sc1
	v_readlane_b32 s29, v240, 60
	s_mov_b32 exec_lo, -1
	s_mov_b32 exec_hi, 0
	v_mbcnt_lo_u32_b32 v2, -1, 0
	s_cmp_lg_u32 s29, 0
	s_cbranch_scc1 .Lnc4_have
	v_lshlrev_b32_e32 v3, 8, v2
	v_add_u32_e32 v3, 0x400, v3
	global_load_dword v4, v3, s[24:25] sc0 sc1
	s_waitcnt vmcnt(0)
	v_readlane_b32 s29, v4, s27
	v_cmp_ne_u32_e32 vcc, 0, v4
	s_nop 3
	s_and_b32 s28, vcc_lo, 0xffff
	v_writelane_b32 v240, s29, 60
	v_writelane_b32 v240, s28, 59

.Lnc4_okf:
.Lnc4_done:
.LBB0_612:
	s_or_b64 exec, exec, s[0:1]
	v_readlane_b32 s0, v243, 45
	v_readlane_b32 s1, v243, 46
	s_andn2_b64 vcc, exec, s[0:1]
	v_readlane_b32 s0, v240, 27
	v_readlane_b32 s1, v240, 28
	s_mov_b32 s1, s85
	v_writelane_b32 v240, s0, 27
	s_barrier
	s_nop 0
	v_writelane_b32 v240, s1, 28
	s_cbranch_vccnz .LBB0_789
	v_mov_b32_e32 v0, v166
	s_barrier
	v_readlane_b32 s24, v242, 26
	v_lshlrev_b32_e32 v2, 4, v0
	v_and_b32_e32 v3, 32, v0
	v_ashrrev_i32_e32 v1, 6, v0
	v_bitop3_b32 v2, v2, v3, 48 bitop3:0x6c
	v_lshlrev_b32_e32 v0, 8, v0
	v_lshrrev_b32_e32 v2, 1, v2
	v_and_b32_e32 v0, 0x3c00, v0
	v_lshlrev_b32_e32 v3, 14, v1
	v_or3_b32 v64, v3, v0, v2
	v_add_u32_e32 v0, 0x20000, v64
	v_lshlrev_b32_e32 v10, 10, v1
	v_mov_b32_e32 v1, v65
	v_lshlrev_b64 v[2:3], 1, v[64:65]
	v_readlane_b32 s25, v242, 27
	v_readfirstlane_b32 s0, v10
	v_lshlrev_b64 v[0:1], 1, v[0:1]
	v_add_u32_e32 v8, 0x2000, v10
	v_lshl_add_u64 v[4:5], s[24:25], 0, v[2:3]
	s_mov_b32 m0, s0
	v_lshl_add_u64 v[6:7], s[24:25], 0, v[0:1]
	v_readfirstlane_b32 s0, v8
	v_readlane_b32 s24, v241, 62
	v_add_u32_e32 v8, 0x4000, v10
	global_load_lds_dwordx4 v[4:5], off
	s_mov_b32 m0, s0
	v_readlane_b32 s25, v241, 63
	v_readfirstlane_b32 s0, v8
	v_add_u32_e32 v8, 0x6000, v10
	global_load_lds_dwordx4 v[6:7], off
	v_lshl_add_u64 v[2:3], s[24:25], 0, v[2:3]
	s_mov_b32 m0, s0
	v_readfirstlane_b32 s0, v8
	v_add_u32_e32 v11, 0x8000, v10
	global_load_lds_dwordx4 v[2:3], off
	v_lshl_add_u64 v[0:1], s[24:25], 0, v[0:1]
	s_mov_b32 m0, s0
	v_readfirstlane_b32 s0, v11
	v_add_u32_e32 v11, 0xa000, v10
	global_load_lds_dwordx4 v[0:1], off
	v_lshl_add_u64 v[8:9], v[4:5], 0, 64
	s_mov_b32 m0, s0
	v_readfirstlane_b32 s0, v11
	v_add_u32_e32 v11, 0xc000, v10
	global_load_lds_dwordx4 v[8:9], off
	v_lshl_add_u64 v[8:9], v[6:7], 0, 64
	s_mov_b32 m0, s0
	v_readfirstlane_b32 s0, v11
	v_add_u32_e32 v11, 0xe000, v10
	global_load_lds_dwordx4 v[8:9], off
	v_lshl_add_u64 v[8:9], v[2:3], 0, 64
	s_mov_b32 m0, s0
	v_readfirstlane_b32 s0, v11
	v_add_u32_e32 v11, 0x10000, v10
	global_load_lds_dwordx4 v[8:9], off
	v_lshl_add_u64 v[8:9], v[0:1], 0, 64
	s_mov_b32 m0, s0
	v_readfirstlane_b32 s0, v11
	v_add_u32_e32 v11, 0x12000, v10
	global_load_lds_dwordx4 v[8:9], off
	v_lshl_add_u64 v[8:9], v[4:5], 0, s[34:35]
	s_mov_b32 m0, s0
	v_readfirstlane_b32 s0, v11
	v_add_u32_e32 v11, 0x14000, v10
	global_load_lds_dwordx4 v[8:9], off
	v_lshl_add_u64 v[8:9], v[6:7], 0, s[34:35]
	s_mov_b32 m0, s0
	v_readfirstlane_b32 s0, v11
	v_add_u32_e32 v11, 0x16000, v10
	global_load_lds_dwordx4 v[8:9], off
	v_lshl_add_u64 v[8:9], v[2:3], 0, s[34:35]
	s_mov_b32 m0, s0
	v_readfirstlane_b32 s0, v11
	global_load_lds_dwordx4 v[8:9], off
	v_lshl_add_u64 v[8:9], v[0:1], 0, s[34:35]
	s_mov_b32 m0, s0
	v_lshl_add_u64 v[4:5], v[4:5], 0, s[82:83]
	global_load_lds_dwordx4 v[8:9], off
	v_add_u32_e32 v8, 0x18000, v10
	v_lshl_add_u64 v[2:3], v[2:3], 0, s[82:83]
	v_readfirstlane_b32 s0, v8
	s_mov_b32 m0, s0
	v_lshl_add_u64 v[0:1], v[0:1], 0, s[82:83]
	global_load_lds_dwordx4 v[4:5], off
	v_lshl_add_u64 v[4:5], v[6:7], 0, s[82:83]
	v_add_u32_e32 v6, 0x1a000, v10
	v_readlane_b32 s24, v244, 0
	v_readfirstlane_b32 s0, v6
	s_mov_b32 m0, s0
	v_readlane_b32 s25, v244, 1
	global_load_lds_dwordx4 v[4:5], off
	v_add_u32_e32 v4, 0x1c000, v10
	s_mov_b32 s78, 1
	v_readfirstlane_b32 s0, v4
	s_mov_b32 m0, s0
	s_mov_b32 s79, 0
	global_load_lds_dwordx4 v[2:3], off
	v_add_u32_e32 v2, 0x1e000, v10
	v_readlane_b32 s80, v242, 28
	v_readfirstlane_b32 s0, v2
	s_mov_b32 m0, s0
	v_readlane_b32 s0, v240, 27
	global_load_lds_dwordx4 v[0:1], off
	v_readlane_b32 s1, v240, 28
	s_lshl_b64 s[0:1], s[0:1], 20
	s_add_u32 s44, s24, s0
	s_addc_u32 s45, s25, s1
	v_readlane_b32 s28, v242, 24
	v_readlane_b32 s29, v242, 25
	s_branch .LBB0_615

.LBB0_789:
	s_waitcnt vmcnt(0)
	s_waitcnt vmcnt(0) lgkmcnt(0)
	s_barrier
	s_and_saveexec_b64 s[0:1], s[74:75]
	s_cbranch_execz .LBB0_842
	s_waitcnt vmcnt(0) lgkmcnt(0)
	v_readlane_b32 s26, v240, 63
	v_readlane_b32 s27, v240, 61
	v_readlane_b32 s28, v240, 62
	s_add_u32 s24, s92, 0xb500900
	s_addc_u32 s25, s93, 0
	s_add_i32 s26, s26, 1
	s_nop 1
	v_writelane_b32 v240, s26, 63
	v_mov_b32_e32 v0, s27
	v_lshlrev_b32_e32 v0, 7, v0
	v_lshl_add_u32 v0, s28, 2, v0
	v_add_u32_e32 v0, 0x1400, v0
	v_mov_b32_e32 v1, s26
	global_store_dword v0, v1, s[24:25]
	s_cmp_lg_u32 s28, 0
	s_cbranch_scc1 .Lnc5_f
	buffer_inv sc1
	v_readlane_b32 s29, v240, 60
	s_mov_b32 exec_lo, -1
	s_mov_b32 exec_hi, 0
	v_mbcnt_lo_u32_b32 v2, -1, 0
	s_cmp_lg_u32 s29, 0
	s_cbranch_scc1 .Lnc5_have
	v_lshlrev_b32_e32 v3, 8, v2
	v_add_u32_e32 v3, 0x400, v3
	global_load_dword v4, v3, s[24:25] sc0 sc1
	s_waitcnt vmcnt(0)
	v_readlane_b32 s29, v4, s27
	v_cmp_ne_u32_e32 vcc, 0, v4
	s_nop 3
	s_and_b32 s28, vcc_lo, 0xffff
	v_writelane_b32 v240, s29, 60
	v_writelane_b32 v240, s28, 59

.Lnc5_okf:
.Lnc5_done:
.LBB0_842:
	s_or_b64 exec, exec, s[0:1]
	v_readlane_b32 s26, v240, 27
	s_lshl_b32 s0, s26, 1
	v_readlane_b32 s1, v241, 30
	s_add_i32 s84, s0, s1
	s_lshl_b64 s[38:39], s[84:85], 2
	v_readlane_b32 s0, v243, 47
	s_add_u32 s24, s0, s38
	v_readlane_b32 s0, v243, 48
	s_addc_u32 s25, s0, s39
	s_cmp_eq_u32 s26, 0
	s_cselect_b64 s[78:79], -1, 0
	s_and_b64 s[0:1], s[78:79], exec
	s_cselect_b32 s64, 0x80, 0
	s_or_b32 s65, s64, 0xa00
	s_barrier
	v_readlane_b32 s27, v240, 28
	s_branch .LBB0_845

.LBB0_948:
	s_waitcnt vmcnt(0)
	s_waitcnt lgkmcnt(0)
	s_barrier
	s_and_saveexec_b64 s[0:1], s[74:75]
	s_cbranch_execz .LBB0_1001
	s_waitcnt vmcnt(0) lgkmcnt(0)
	v_readlane_b32 s26, v240, 63
	v_readlane_b32 s27, v240, 61
	v_readlane_b32 s28, v240, 62
	s_add_u32 s24, s92, 0xb500900
	s_addc_u32 s25, s93, 0
	s_add_i32 s26, s26, 1
	s_nop 1
	v_writelane_b32 v240, s26, 63
	v_mov_b32_e32 v0, s27
	v_lshlrev_b32_e32 v0, 7, v0
	v_lshl_add_u32 v0, s28, 2, v0
	v_add_u32_e32 v0, 0x1400, v0
	v_mov_b32_e32 v1, s26
	global_store_dword v0, v1, s[24:25]
	s_cmp_lg_u32 s28, 0
	s_cbranch_scc1 .Lnc6_f
	buffer_inv sc1
	v_readlane_b32 s29, v240, 60
	s_mov_b32 exec_lo, -1
	s_mov_b32 exec_hi, 0
	v_mbcnt_lo_u32_b32 v2, -1, 0
	s_cmp_lg_u32 s29, 0
	s_cbranch_scc1 .Lnc6_have
	v_lshlrev_b32_e32 v3, 8, v2
	v_add_u32_e32 v3, 0x400, v3
	global_load_dword v4, v3, s[24:25] sc0 sc1
	s_waitcnt vmcnt(0)
	v_readlane_b32 s29, v4, s27
	v_cmp_ne_u32_e32 vcc, 0, v4
	s_nop 3
	s_and_b32 s28, vcc_lo, 0xffff
	v_writelane_b32 v240, s29, 60
	v_writelane_b32 v240, s28, 59

.Lnc6_okf:
.Lnc6_done:
.LBB0_1001:
	s_or_b64 exec, exec, s[0:1]
	s_add_u32 s0, s92, s38
	s_addc_u32 s1, s93, s39
	s_add_u32 s24, s0, 0xb500104
	s_addc_u32 s25, s1, 0
	s_barrier
	s_branch .LBB0_1004

.LBB0_1059:
	s_andn2_b64 vcc, exec, s[78:79]
	s_cbranch_vccnz .LBB0_1117
	s_waitcnt vmcnt(0)
	s_barrier
	s_and_saveexec_b64 s[0:1], s[74:75]
	v_readlane_b32 s2, v241, 19
	s_branch .LBB0_1113
	s_waitcnt vmcnt(0) lgkmcnt(0)
	v_readlane_b32 s26, v240, 63
	v_readlane_b32 s27, v240, 61
	v_readlane_b32 s28, v240, 62
	s_add_u32 s24, s92, 0xb500900
	s_addc_u32 s25, s93, 0
	s_add_i32 s26, s26, 1
	s_nop 1
	v_writelane_b32 v240, s26, 63
	v_mov_b32_e32 v0, s27
	v_lshlrev_b32_e32 v0, 7, v0
	v_lshl_add_u32 v0, s28, 2, v0
	v_add_u32_e32 v0, 0x1400, v0
	v_mov_b32_e32 v1, s26
	global_store_dword v0, v1, s[24:25]
	s_cmp_lg_u32 s28, 0
	s_cbranch_scc1 .Lnc7_f
	buffer_inv sc1
	v_readlane_b32 s29, v240, 60
	s_mov_b32 exec_lo, -1
	s_mov_b32 exec_hi, 0
	v_mbcnt_lo_u32_b32 v2, -1, 0
	s_cmp_lg_u32 s29, 0
	s_cbranch_scc1 .Lnc7_have
	v_lshlrev_b32_e32 v3, 8, v2
	v_add_u32_e32 v3, 0x400, v3
	global_load_dword v4, v3, s[24:25] sc0 sc1
	s_waitcnt vmcnt(0)
	v_readlane_b32 s29, v4, s27
	v_cmp_ne_u32_e32 vcc, 0, v4
	s_nop 3
	s_and_b32 s28, vcc_lo, 0xffff
	v_writelane_b32 v240, s29, 60
	v_writelane_b32 v240, s28, 59

.Lnc7_okf:
.Lnc7_done:
.LBB0_1113:
	s_or_b64 exec, exec, s[0:1]
	v_readlane_b32 s0, v243, 63
	v_readlane_b32 s1, v242, 0
	s_andn2_b64 vcc, exec, s[0:1]
	s_mov_b32 s24, s2
	s_barrier
	s_cbranch_vccnz .LBB0_1117

.LBB0_1117:
	s_waitcnt vmcnt(0)
	s_barrier
	s_and_saveexec_b64 s[0:1], s[74:75]
	s_cbranch_execz .LBB0_1170
	s_waitcnt vmcnt(0) lgkmcnt(0)
	v_readlane_b32 s26, v240, 63
	v_readlane_b32 s27, v240, 61
	v_readlane_b32 s28, v240, 62
	s_add_u32 s24, s92, 0xb500900
	s_addc_u32 s25, s93, 0
	s_add_i32 s26, s26, 1
	s_nop 1
	v_writelane_b32 v240, s26, 63
	v_mov_b32_e32 v0, s27
	v_lshlrev_b32_e32 v0, 7, v0
	v_lshl_add_u32 v0, s28, 2, v0
	v_add_u32_e32 v0, 0x1400, v0
	v_mov_b32_e32 v1, s26
	global_store_dword v0, v1, s[24:25]
	s_cmp_lg_u32 s28, 0
	s_cbranch_scc1 .Lnc8_f
	buffer_inv sc1
	v_readlane_b32 s29, v240, 60
	s_mov_b32 exec_lo, -1
	s_mov_b32 exec_hi, 0
	v_mbcnt_lo_u32_b32 v2, -1, 0
	s_cmp_lg_u32 s29, 0
	s_cbranch_scc1 .Lnc8_have
	v_lshlrev_b32_e32 v3, 8, v2
	v_add_u32_e32 v3, 0x400, v3
	global_load_dword v4, v3, s[24:25] sc0 sc1
	s_waitcnt vmcnt(0)
	v_readlane_b32 s29, v4, s27
	v_cmp_ne_u32_e32 vcc, 0, v4
	s_nop 3
	s_and_b32 s28, vcc_lo, 0xffff
	v_writelane_b32 v240, s29, 60
	v_writelane_b32 v240, s28, 59

.Lnc8_okf:
.Lnc8_done:
.LBB0_1170:
	s_or_b64 exec, exec, s[0:1]
	v_readlane_b32 s0, v240, 27
	v_readlane_b32 s1, v240, 28
	s_lshl_b64 s[0:1], s[0:1], 23
	v_readlane_b32 s24, v242, 1
	v_readlane_b32 s25, v242, 2
	s_add_u32 s84, s24, s0
	s_addc_u32 s74, s25, s1
	s_mov_b32 s75, 0
	s_barrier
	s_branch .LBB0_1173

.LBB0_1212:
	s_waitcnt vmcnt(0)
	v_readlane_b32 s74, v241, 17
	v_readlane_b32 s75, v241, 18
	s_barrier
	s_and_saveexec_b64 s[0:1], s[74:75]
	v_readlane_b32 s2, v241, 19
	s_cbranch_execz .LBB0_1265
	s_waitcnt vmcnt(0) lgkmcnt(0)
	v_readlane_b32 s26, v240, 63
	v_readlane_b32 s27, v240, 61
	v_readlane_b32 s28, v240, 62
	s_add_u32 s24, s92, 0xb500900
	s_addc_u32 s25, s93, 0
	s_add_i32 s26, s26, 1
	s_nop 1
	v_writelane_b32 v240, s26, 63
	v_mov_b32_e32 v0, s27
	v_lshlrev_b32_e32 v0, 7, v0
	v_lshl_add_u32 v0, s28, 2, v0
	v_add_u32_e32 v0, 0x1400, v0
	v_mov_b32_e32 v1, s26
	global_store_dword v0, v1, s[24:25]
	s_cmp_lg_u32 s28, 0
	s_cbranch_scc1 .Lnc9_f
	buffer_inv sc1
	v_readlane_b32 s29, v240, 60
	s_mov_b32 exec_lo, -1
	s_mov_b32 exec_hi, 0
	v_mbcnt_lo_u32_b32 v2, -1, 0
	s_cmp_lg_u32 s29, 0
	s_cbranch_scc1 .Lnc9_have
	v_lshlrev_b32_e32 v3, 8, v2
	v_add_u32_e32 v3, 0x400, v3
	global_load_dword v4, v3, s[24:25] sc0 sc1
	s_waitcnt vmcnt(0)
	v_readlane_b32 s29, v4, s27
	v_cmp_ne_u32_e32 vcc, 0, v4
	s_nop 3
	s_and_b32 s28, vcc_lo, 0xffff
	v_writelane_b32 v240, s29, 60
	v_writelane_b32 v240, s28, 59

.Lnc9_okf:
.Lnc9_done:
.LBB0_1265:
	s_or_b64 exec, exec, s[0:1]
	v_readlane_b32 s44, v245, 48
	v_readlane_b32 s58, v245, 62
	v_readlane_b32 s0, v240, 29
	v_readlane_b32 s59, v245, 63
	v_readlane_b32 s1, v240, 30
	s_add_u32 s38, s58, s0
	s_addc_u32 s39, s59, s1
	v_readlane_b32 s0, v242, 5
	v_readlane_b32 s1, v242, 6
	v_readlane_b32 s48, v245, 52
	v_readlane_b32 s49, v245, 53
	v_cndmask_b32_e64 v0, 0, 1, s[0:1]
	v_cmp_ne_u32_e64 s[48:49], 1, v0
	s_andn2_b64 vcc, exec, s[0:1]
	v_readlane_b32 s45, v245, 49
	v_readlane_b32 s46, v245, 50
	v_readlane_b32 s47, v245, 51
	v_readlane_b32 s50, v245, 54
	v_readlane_b32 s51, v245, 55
	v_readlane_b32 s52, v245, 56
	v_readlane_b32 s53, v245, 57
	v_readlane_b32 s54, v245, 58
	v_readlane_b32 s55, v245, 59
	v_readlane_b32 s56, v245, 60
	v_readlane_b32 s57, v245, 61
	s_barrier
	s_cbranch_vccnz .LBB0_1298
	v_mov_b32_e32 v0, v166
	s_barrier
	v_readlane_b32 s24, v242, 33
	v_lshlrev_b32_e32 v2, 4, v0
	v_and_b32_e32 v3, 32, v0
	v_ashrrev_i32_e32 v1, 6, v0
	v_bitop3_b32 v2, v2, v3, 48 bitop3:0x6c
	v_lshlrev_b32_e32 v0, 8, v0
	v_lshrrev_b32_e32 v2, 1, v2
	v_and_b32_e32 v0, 0x3c00, v0
	v_lshlrev_b32_e32 v3, 14, v1
	v_or3_b32 v64, v3, v0, v2
	v_add_u32_e32 v0, 0x20000, v64
	v_lshlrev_b32_e32 v10, 10, v1
	v_mov_b32_e32 v1, v65
	v_lshlrev_b64 v[2:3], 1, v[64:65]
	v_readlane_b32 s25, v242, 34
	v_readfirstlane_b32 s0, v10
	v_lshlrev_b64 v[0:1], 1, v[0:1]
	v_add_u32_e32 v8, 0x2000, v10
	v_lshl_add_u64 v[4:5], s[24:25], 0, v[2:3]
	s_mov_b32 m0, s0
	v_lshl_add_u64 v[6:7], s[24:25], 0, v[0:1]
	v_readfirstlane_b32 s0, v8
	v_readlane_b32 s24, v240, 2
	v_add_u32_e32 v8, 0x4000, v10
	global_load_lds_dwordx4 v[4:5], off
	s_mov_b32 m0, s0
	v_readlane_b32 s25, v240, 3
	v_readfirstlane_b32 s0, v8
	v_add_u32_e32 v8, 0x6000, v10
	global_load_lds_dwordx4 v[6:7], off
	v_lshl_add_u64 v[2:3], s[24:25], 0, v[2:3]
	s_mov_b32 m0, s0
	v_readfirstlane_b32 s0, v8
	v_add_u32_e32 v11, 0x8000, v10
	global_load_lds_dwordx4 v[2:3], off
	v_lshl_add_u64 v[0:1], s[24:25], 0, v[0:1]
	s_mov_b32 m0, s0
	v_readfirstlane_b32 s0, v11
	v_add_u32_e32 v11, 0xa000, v10
	global_load_lds_dwordx4 v[0:1], off
	v_lshl_add_u64 v[8:9], v[4:5], 0, 64
	s_mov_b32 m0, s0
	v_readfirstlane_b32 s0, v11
	v_add_u32_e32 v11, 0xc000, v10
	global_load_lds_dwordx4 v[8:9], off
	v_lshl_add_u64 v[8:9], v[6:7], 0, 64
	s_mov_b32 m0, s0
	v_readfirstlane_b32 s0, v11
	v_add_u32_e32 v11, 0xe000, v10
	global_load_lds_dwordx4 v[8:9], off
	v_lshl_add_u64 v[8:9], v[2:3], 0, 64
	s_mov_b32 m0, s0
	v_readfirstlane_b32 s0, v11
	v_add_u32_e32 v11, 0x10000, v10
	global_load_lds_dwordx4 v[8:9], off
	v_lshl_add_u64 v[8:9], v[0:1], 0, 64
	s_mov_b32 m0, s0
	v_readfirstlane_b32 s0, v11
	v_add_u32_e32 v11, 0x12000, v10
	global_load_lds_dwordx4 v[8:9], off
	v_lshl_add_u64 v[8:9], v[4:5], 0, s[34:35]
	s_mov_b32 m0, s0
	v_readfirstlane_b32 s0, v11
	v_add_u32_e32 v11, 0x14000, v10
	global_load_lds_dwordx4 v[8:9], off
	v_lshl_add_u64 v[8:9], v[6:7], 0, s[34:35]
	s_mov_b32 m0, s0
	v_readfirstlane_b32 s0, v11
	v_add_u32_e32 v11, 0x16000, v10
	global_load_lds_dwordx4 v[8:9], off
	v_lshl_add_u64 v[8:9], v[2:3], 0, s[34:35]
	s_mov_b32 m0, s0
	v_readfirstlane_b32 s0, v11
	global_load_lds_dwordx4 v[8:9], off
	v_lshl_add_u64 v[8:9], v[0:1], 0, s[34:35]
	s_mov_b32 m0, s0
	v_lshl_add_u64 v[4:5], v[4:5], 0, s[82:83]
	global_load_lds_dwordx4 v[8:9], off
	v_add_u32_e32 v8, 0x18000, v10
	v_lshl_add_u64 v[2:3], v[2:3], 0, s[82:83]
	v_readfirstlane_b32 s0, v8
	s_mov_b32 m0, s0
	v_lshl_add_u64 v[0:1], v[0:1], 0, s[82:83]
	global_load_lds_dwordx4 v[4:5], off
	v_lshl_add_u64 v[4:5], v[6:7], 0, s[82:83]
	v_add_u32_e32 v6, 0x1a000, v10
	s_mov_b32 s74, 1
	v_readfirstlane_b32 s0, v6
	s_mov_b32 m0, s0
	s_mov_b32 s75, 0
	global_load_lds_dwordx4 v[4:5], off
	v_add_u32_e32 v4, 0x1c000, v10
	v_readlane_b32 s30, v242, 43
	v_readfirstlane_b32 s0, v4
	s_mov_b32 m0, s0
	v_readlane_b32 s64, v242, 53
	global_load_lds_dwordx4 v[2:3], off
	v_add_u32_e32 v2, 0x1e000, v10
	v_readlane_b32 s31, v242, 44
	v_readfirstlane_b32 s0, v2
	s_mov_b32 m0, s0
	v_readlane_b32 s65, v242, 54
	global_load_lds_dwordx4 v[0:1], off
	s_branch .LBB0_1268

.LBB0_1298:
	s_waitcnt vmcnt(0)
	s_waitcnt lgkmcnt(0)
	s_barrier
	s_and_saveexec_b64 s[0:1], s[74:75]
	s_movk_i32 s46, 0x3fff
	s_cbranch_execz .LBB0_1351
	s_waitcnt vmcnt(0) lgkmcnt(0)
	v_readlane_b32 s26, v240, 63
	v_readlane_b32 s27, v240, 61
	v_readlane_b32 s28, v240, 62
	s_add_u32 s24, s92, 0xb500900
	s_addc_u32 s25, s93, 0
	s_add_i32 s26, s26, 1
	s_nop 1
	v_writelane_b32 v240, s26, 63
	v_mov_b32_e32 v0, s27
	v_lshlrev_b32_e32 v0, 7, v0
	v_lshl_add_u32 v0, s28, 2, v0
	v_add_u32_e32 v0, 0x1400, v0
	v_mov_b32_e32 v1, s26
	global_store_dword v0, v1, s[24:25]
	s_cmp_lg_u32 s28, 0
	s_cbranch_scc1 .Lnc10_f
	buffer_inv sc1
	v_readlane_b32 s29, v240, 60
	s_mov_b32 exec_lo, -1
	s_mov_b32 exec_hi, 0
	v_mbcnt_lo_u32_b32 v2, -1, 0
	s_cmp_lg_u32 s29, 0
	s_cbranch_scc1 .Lnc10_have
	v_lshlrev_b32_e32 v3, 8, v2
	v_add_u32_e32 v3, 0x400, v3
	global_load_dword v4, v3, s[24:25] sc0 sc1
	s_waitcnt vmcnt(0)
	v_readlane_b32 s29, v4, s27
	v_cmp_ne_u32_e32 vcc, 0, v4
	s_nop 3
	s_and_b32 s28, vcc_lo, 0xffff
	v_writelane_b32 v240, s29, 60
	v_writelane_b32 v240, s28, 59

.Lnc10_okf:
.Lnc10_done:
.LBB0_1351:
	s_or_b64 exec, exec, s[0:1]
	s_branch .LBB0_1407
	v_mov_b32_e32 v0, v166
	s_barrier
	v_readlane_b32 s0, v244, 3
	v_ashrrev_i32_e32 v1, 6, v0
	s_nop 0
	v_add_u32_e32 v24, s0, v1
	s_movk_i32 s0, 0x4000
	v_cmp_gt_i32_e32 vcc, s0, v24
	s_and_saveexec_b64 s[24:25], vcc
	s_cbranch_execz .LBB0_1354
	v_and_b32_e32 v16, 63, v0
	v_readlane_b32 s0, v241, 41
	v_lshlrev_b32_e32 v64, 4, v16
	v_readlane_b32 s1, v241, 42
	s_nop 4
	global_load_dwordx4 v[0:3], v64, s[0:1]
	global_load_dwordx4 v[4:7], v64, s[0:1] offset:1024
	global_load_dwordx4 v[8:11], v64, s[0:1] offset:2048
	global_load_dwordx4 v[12:15], v64, s[0:1] offset:3072
	v_cmp_lt_i32_e32 vcc, v157, v168
	v_lshlrev_b32_e32 v16, 2, v16
	v_or_b32_e32 v18, 0x100, v16
	v_cndmask_b32_e32 v17, v155, v157, vcc
	v_cmp_lt_i32_e32 vcc, v169, v168
	v_lshlrev_b32_e32 v37, 2, v17
	v_or_b32_e32 v20, 0x200, v16
	v_cndmask_b32_e32 v17, v155, v169, vcc
	v_or_b32_e32 v22, 0x300, v16
	v_lshlrev_b32_e32 v38, 2, v17
	v_lshl_add_u64 v[26:27], s[38:39], 0, v[64:65]
	s_mov_b64 s[28:29], 0
	v_lshlrev_b32_e32 v64, 1, v16
	v_lshlrev_b32_e32 v28, 1, v18
	v_lshlrev_b32_e32 v30, 1, v20
	v_lshlrev_b32_e32 v32, 1, v22

.LBB0_1354:
	s_or_b64 exec, exec, s[24:25]
	s_waitcnt vmcnt(0)
	s_barrier
	s_and_saveexec_b64 s[0:1], s[74:75]
	s_cbranch_execz .LBB0_1407
	s_waitcnt vmcnt(0) lgkmcnt(0)
	v_readlane_b32 s26, v240, 63
	v_readlane_b32 s27, v240, 61
	v_readlane_b32 s28, v240, 62
	s_add_u32 s24, s92, 0xb500900
	s_addc_u32 s25, s93, 0
	s_add_i32 s26, s26, 1
	s_nop 1
	v_writelane_b32 v240, s26, 63
	v_mov_b32_e32 v0, s27
	v_lshlrev_b32_e32 v0, 7, v0
	v_lshl_add_u32 v0, s28, 2, v0
	v_add_u32_e32 v0, 0x1400, v0
	v_mov_b32_e32 v1, s26
	global_store_dword v0, v1, s[24:25]
	s_cmp_lg_u32 s28, 0
	s_cbranch_scc1 .Lnc11_f
	buffer_inv sc1
	v_readlane_b32 s29, v240, 60
	s_mov_b32 exec_lo, -1
	s_mov_b32 exec_hi, 0
	v_mbcnt_lo_u32_b32 v2, -1, 0
	s_cmp_lg_u32 s29, 0
	s_cbranch_scc1 .Lnc11_have
	v_lshlrev_b32_e32 v3, 8, v2
	v_add_u32_e32 v3, 0x400, v3
	global_load_dword v4, v3, s[24:25] sc0 sc1
	s_waitcnt vmcnt(0)
	v_readlane_b32 s29, v4, s27
	v_cmp_ne_u32_e32 vcc, 0, v4
	s_nop 3
	s_and_b32 s28, vcc_lo, 0xffff
	v_writelane_b32 v240, s29, 60
	v_writelane_b32 v240, s28, 59

.Lnc11_okf:
.Lnc11_done:
.LBB0_1407:
	s_or_b64 exec, exec, s[0:1]
	v_readlane_b32 s0, v244, 20
	v_readlane_b32 s1, v244, 21
	s_andn2_b64 vcc, exec, s[0:1]
	s_barrier
	s_cbranch_vccnz .LBB0_1439
	v_readlane_b32 s0, v240, 27
	s_lshl_b32 s44, s0, 2
	s_mov_b32 s45, s2
	s_mov_b32 s64, s2
	v_readlane_b32 s1, v240, 28
	s_branch .LBB0_1410

.Lnc12_okf:
.Lnc12_done:
.LBB0_1492:
	s_or_b64 exec, exec, s[0:1]
	s_and_b64 vcc, exec, s[48:49]
	s_barrier
	s_cbranch_vccnz .LBB0_1525
	v_mov_b32_e32 v0, v166
	s_barrier
	v_readlane_b32 s24, v242, 37
	v_lshlrev_b32_e32 v2, 4, v0
	v_and_b32_e32 v3, 32, v0
	v_ashrrev_i32_e32 v1, 6, v0
	v_bitop3_b32 v2, v2, v3, 48 bitop3:0x6c
	v_lshlrev_b32_e32 v0, 8, v0
	v_lshrrev_b32_e32 v2, 1, v2
	v_and_b32_e32 v0, 0x3c00, v0
	v_lshlrev_b32_e32 v3, 14, v1
	v_or3_b32 v64, v3, v0, v2
	v_add_u32_e32 v0, 0x20000, v64
	v_lshlrev_b32_e32 v10, 10, v1
	v_mov_b32_e32 v1, v65
	v_lshlrev_b64 v[2:3], 1, v[64:65]
	v_readlane_b32 s25, v242, 38
	v_readfirstlane_b32 s0, v10
	v_lshlrev_b64 v[0:1], 1, v[0:1]
	v_add_u32_e32 v8, 0x2000, v10
	v_lshl_add_u64 v[4:5], s[24:25], 0, v[2:3]
	s_mov_b32 m0, s0
	v_lshl_add_u64 v[6:7], s[24:25], 0, v[0:1]
	v_readfirstlane_b32 s0, v8
	v_readlane_b32 s24, v240, 6
	v_add_u32_e32 v8, 0x4000, v10
	global_load_lds_dwordx4 v[4:5], off
	s_mov_b32 m0, s0
	v_readlane_b32 s25, v240, 7
	v_readfirstlane_b32 s0, v8
	v_add_u32_e32 v8, 0x6000, v10
	global_load_lds_dwordx4 v[6:7], off
	v_lshl_add_u64 v[2:3], s[24:25], 0, v[2:3]
	s_mov_b32 m0, s0
	v_readfirstlane_b32 s0, v8
	v_add_u32_e32 v11, 0x8000, v10
	global_load_lds_dwordx4 v[2:3], off
	v_lshl_add_u64 v[0:1], s[24:25], 0, v[0:1]
	s_mov_b32 m0, s0
	v_readfirstlane_b32 s0, v11
	v_add_u32_e32 v11, 0xa000, v10
	global_load_lds_dwordx4 v[0:1], off
	v_lshl_add_u64 v[8:9], v[4:5], 0, 64
	s_mov_b32 m0, s0
	v_readfirstlane_b32 s0, v11
	v_add_u32_e32 v11, 0xc000, v10
	global_load_lds_dwordx4 v[8:9], off
	v_lshl_add_u64 v[8:9], v[6:7], 0, 64
	s_mov_b32 m0, s0
	v_readfirstlane_b32 s0, v11
	v_add_u32_e32 v11, 0xe000, v10
	global_load_lds_dwordx4 v[8:9], off
	v_lshl_add_u64 v[8:9], v[2:3], 0, 64
	s_mov_b32 m0, s0
	v_readfirstlane_b32 s0, v11
	v_add_u32_e32 v11, 0x10000, v10
	global_load_lds_dwordx4 v[8:9], off
	v_lshl_add_u64 v[8:9], v[0:1], 0, 64
	s_mov_b32 m0, s0
	v_readfirstlane_b32 s0, v11
	v_add_u32_e32 v11, 0x12000, v10
	global_load_lds_dwordx4 v[8:9], off
	v_lshl_add_u64 v[8:9], v[4:5], 0, s[34:35]
	s_mov_b32 m0, s0
	v_readfirstlane_b32 s0, v11
	v_add_u32_e32 v11, 0x14000, v10
	global_load_lds_dwordx4 v[8:9], off
	v_lshl_add_u64 v[8:9], v[6:7], 0, s[34:35]
	s_mov_b32 m0, s0
	v_readfirstlane_b32 s0, v11
	v_add_u32_e32 v11, 0x16000, v10
	global_load_lds_dwordx4 v[8:9], off
	v_lshl_add_u64 v[8:9], v[2:3], 0, s[34:35]
	s_mov_b32 m0, s0
	v_readfirstlane_b32 s0, v11
	global_load_lds_dwordx4 v[8:9], off
	v_lshl_add_u64 v[8:9], v[0:1], 0, s[34:35]
	s_mov_b32 m0, s0
	v_lshl_add_u64 v[4:5], v[4:5], 0, s[82:83]
	global_load_lds_dwordx4 v[8:9], off
	v_add_u32_e32 v8, 0x18000, v10
	v_lshl_add_u64 v[2:3], v[2:3], 0, s[82:83]
	v_readfirstlane_b32 s0, v8
	s_mov_b32 m0, s0
	v_lshl_add_u64 v[0:1], v[0:1], 0, s[82:83]
	global_load_lds_dwordx4 v[4:5], off
	v_lshl_add_u64 v[4:5], v[6:7], 0, s[82:83]
	v_add_u32_e32 v6, 0x1a000, v10
	s_mov_b32 s64, 1
	v_readfirstlane_b32 s0, v6
	s_mov_b32 m0, s0
	s_mov_b32 s65, 0
	global_load_lds_dwordx4 v[4:5], off
	v_add_u32_e32 v4, 0x1c000, v10
	v_readlane_b32 s24, v242, 53
	v_readfirstlane_b32 s0, v4
	s_mov_b32 m0, s0
	v_readlane_b32 s46, v240, 4
	global_load_lds_dwordx4 v[2:3], off
	v_add_u32_e32 v2, 0x1e000, v10
	v_readlane_b32 s25, v242, 54
	v_readfirstlane_b32 s0, v2
	s_mov_b32 m0, s0
	v_readlane_b32 s0, v242, 43
	global_load_lds_dwordx4 v[0:1], off
	v_readlane_b32 s1, v242, 44
	s_branch .LBB0_1495

.Lnc13_okf:
.Lnc13_done:
.LBB0_1578:
	s_or_b64 exec, exec, s[0:1]
	s_branch .LBB0_1634
	v_mov_b32_e32 v0, v166
	s_barrier
	v_readlane_b32 s0, v244, 3
	v_ashrrev_i32_e32 v1, 6, v0
	s_nop 0
	v_add_u32_e32 v24, s0, v1
	s_movk_i32 s0, 0x4000
	v_cmp_gt_i32_e32 vcc, s0, v24
	s_and_saveexec_b64 s[24:25], vcc
	s_cbranch_execz .LBB0_1581
	v_and_b32_e32 v16, 63, v0
	v_readlane_b32 s0, v241, 46
	v_lshlrev_b32_e32 v64, 4, v16
	v_readlane_b32 s1, v241, 47
	s_nop 4
	global_load_dwordx4 v[0:3], v64, s[0:1]
	global_load_dwordx4 v[4:7], v64, s[0:1] offset:1024
	global_load_dwordx4 v[8:11], v64, s[0:1] offset:2048
	global_load_dwordx4 v[12:15], v64, s[0:1] offset:3072
	v_cmp_lt_i32_e32 vcc, v157, v168
	v_lshlrev_b32_e32 v16, 2, v16
	v_or_b32_e32 v18, 0x100, v16
	v_cndmask_b32_e32 v17, v155, v157, vcc
	v_cmp_lt_i32_e32 vcc, v169, v168
	s_waitcnt vmcnt(26)
	v_lshlrev_b32_e32 v37, 2, v17
	v_or_b32_e32 v20, 0x200, v16
	v_cndmask_b32_e32 v17, v155, v169, vcc
	v_or_b32_e32 v22, 0x300, v16
	v_lshlrev_b32_e32 v38, 2, v17
	v_lshl_add_u64 v[26:27], s[38:39], 0, v[64:65]
	s_mov_b64 s[28:29], 0
	v_lshlrev_b32_e32 v64, 1, v16
	v_lshlrev_b32_e32 v28, 1, v18
	v_lshlrev_b32_e32 v30, 1, v20
	v_lshlrev_b32_e32 v32, 1, v22

.Lnc14_okf:
.Lnc14_done:
.LBB0_1634:
	s_or_b64 exec, exec, s[0:1]
	v_readlane_b32 s0, v242, 15
	v_readlane_b32 s1, v242, 16
	s_andn2_b64 vcc, exec, s[0:1]
	s_barrier
	s_cbranch_vccnz .LBB0_1667
	v_mov_b32_e32 v0, v166
	s_barrier
	v_readlane_b32 s24, v242, 41
	v_lshlrev_b32_e32 v2, 4, v0
	v_and_b32_e32 v3, 32, v0
	v_ashrrev_i32_e32 v1, 6, v0
	v_bitop3_b32 v2, v2, v3, 48 bitop3:0x6c
	v_lshlrev_b32_e32 v0, 8, v0
	v_lshrrev_b32_e32 v2, 1, v2
	v_and_b32_e32 v0, 0x3c00, v0
	v_lshlrev_b32_e32 v3, 14, v1
	v_or3_b32 v64, v3, v0, v2
	v_add_u32_e32 v0, 0x20000, v64
	v_lshlrev_b32_e32 v10, 10, v1
	v_mov_b32_e32 v1, v65
	v_lshlrev_b64 v[2:3], 1, v[64:65]
	v_readlane_b32 s25, v242, 42
	v_readfirstlane_b32 s0, v10
	v_lshlrev_b64 v[0:1], 1, v[0:1]
	v_add_u32_e32 v8, 0x2000, v10
	v_lshl_add_u64 v[4:5], s[24:25], 0, v[2:3]
	s_mov_b32 m0, s0
	v_lshl_add_u64 v[6:7], s[24:25], 0, v[0:1]
	v_readfirstlane_b32 s0, v8
	v_readlane_b32 s24, v240, 10
	v_add_u32_e32 v8, 0x4000, v10
	global_load_lds_dwordx4 v[4:5], off
	s_mov_b32 m0, s0
	v_readlane_b32 s25, v240, 11
	v_readfirstlane_b32 s0, v8
	v_add_u32_e32 v8, 0x6000, v10
	global_load_lds_dwordx4 v[6:7], off
	v_lshl_add_u64 v[2:3], s[24:25], 0, v[2:3]
	s_mov_b32 m0, s0
	v_readfirstlane_b32 s0, v8
	v_add_u32_e32 v11, 0x8000, v10
	global_load_lds_dwordx4 v[2:3], off
	v_lshl_add_u64 v[0:1], s[24:25], 0, v[0:1]
	s_mov_b32 m0, s0
	v_readfirstlane_b32 s0, v11
	v_add_u32_e32 v11, 0xa000, v10
	global_load_lds_dwordx4 v[0:1], off
	v_lshl_add_u64 v[8:9], v[4:5], 0, 64
	s_mov_b32 m0, s0
	v_readfirstlane_b32 s0, v11
	v_add_u32_e32 v11, 0xc000, v10
	global_load_lds_dwordx4 v[8:9], off
	v_lshl_add_u64 v[8:9], v[6:7], 0, 64
	s_mov_b32 m0, s0
	v_readfirstlane_b32 s0, v11
	v_add_u32_e32 v11, 0xe000, v10
	global_load_lds_dwordx4 v[8:9], off
	v_lshl_add_u64 v[8:9], v[2:3], 0, 64
	s_mov_b32 m0, s0
	v_readfirstlane_b32 s0, v11
	v_add_u32_e32 v11, 0x10000, v10
	global_load_lds_dwordx4 v[8:9], off
	v_lshl_add_u64 v[8:9], v[0:1], 0, 64
	s_mov_b32 m0, s0
	v_readfirstlane_b32 s0, v11
	v_add_u32_e32 v11, 0x12000, v10
	global_load_lds_dwordx4 v[8:9], off
	v_lshl_add_u64 v[8:9], v[4:5], 0, s[34:35]
	s_mov_b32 m0, s0
	v_readfirstlane_b32 s0, v11
	v_add_u32_e32 v11, 0x14000, v10
	global_load_lds_dwordx4 v[8:9], off
	v_lshl_add_u64 v[8:9], v[6:7], 0, s[34:35]
	s_mov_b32 m0, s0
	v_readfirstlane_b32 s0, v11
	v_add_u32_e32 v11, 0x16000, v10
	global_load_lds_dwordx4 v[8:9], off
	v_lshl_add_u64 v[8:9], v[2:3], 0, s[34:35]
	s_mov_b32 m0, s0
	v_readfirstlane_b32 s0, v11
	global_load_lds_dwordx4 v[8:9], off
	v_lshl_add_u64 v[8:9], v[0:1], 0, s[34:35]
	s_mov_b32 m0, s0
	v_lshl_add_u64 v[4:5], v[4:5], 0, s[82:83]
	global_load_lds_dwordx4 v[8:9], off
	v_add_u32_e32 v8, 0x18000, v10
	v_lshl_add_u64 v[2:3], v[2:3], 0, s[82:83]
	v_readfirstlane_b32 s0, v8
	s_mov_b32 m0, s0
	v_lshl_add_u64 v[0:1], v[0:1], 0, s[82:83]
	global_load_lds_dwordx4 v[4:5], off
	v_lshl_add_u64 v[4:5], v[6:7], 0, s[82:83]
	v_add_u32_e32 v6, 0x1a000, v10
	s_mov_b32 s64, 1
	v_readfirstlane_b32 s0, v6
	s_mov_b32 m0, s0
	s_mov_b32 s65, 0
	global_load_lds_dwordx4 v[4:5], off
	v_add_u32_e32 v4, 0x1c000, v10
	v_readlane_b32 s28, v242, 39
	v_readfirstlane_b32 s0, v4
	s_mov_b32 m0, s0
	v_readlane_b32 s30, v242, 45
	global_load_lds_dwordx4 v[2:3], off
	v_add_u32_e32 v2, 0x1e000, v10
	v_readlane_b32 s46, v240, 8
	v_readfirstlane_b32 s0, v2
	s_mov_b32 m0, s0
	v_readlane_b32 s29, v242, 40
	global_load_lds_dwordx4 v[0:1], off
	v_readlane_b32 s31, v242, 46
	s_waitcnt vmcnt(0)
	s_branch .LBB0_1637

.Lnc15_okf:
.Lnc15_done:
.LBB0_1720:
	s_or_b64 exec, exec, s[0:1]
	v_mov_b32_e32 v0, v166
	v_readlane_b32 s0, v244, 2
	s_barrier
	s_nop 0
	v_add_u32_e32 v64, s0, v0
	s_mov_b32 s0, 0xb0000
	v_cmp_gt_i32_e32 vcc, s0, v64
	s_and_saveexec_b64 s[24:25], vcc
	s_cbranch_execz .LBB0_1727
	s_mov_b64 s[28:29], 0
	s_branch .LBB0_1723

.Lnc16_okf:
.Lnc16_done:
.LBB0_1780:
	s_or_b64 exec, exec, s[0:1]
	s_and_b64 vcc, exec, s[48:49]
	s_barrier
	s_cbranch_vccnz .LBB0_502
	v_mov_b32_e32 v0, v166
	s_barrier
	s_movk_i32 s0, 0xb00
	v_ashrrev_i32_e32 v1, 6, v0
	v_lshlrev_b32_e32 v2, 4, v0
	v_and_b32_e32 v3, 32, v0
	v_lshrrev_b32_e32 v0, 2, v0
	v_bitop3_b32 v2, v2, v3, 48 bitop3:0x6c
	v_lshlrev_b32_e32 v3, 4, v1
	v_and_or_b32 v0, v0, 15, v3
	v_lshrrev_b32_e32 v2, 1, v2
	v_mul_lo_u32 v0, v0, s0
	v_or_b32_e32 v64, v0, v2
	v_add_u32_e32 v0, 0x58000, v64
	v_lshlrev_b32_e32 v10, 10, v1
	v_mov_b32_e32 v1, v65
	v_readlane_b32 s24, v242, 51
	v_lshlrev_b64 v[2:3], 1, v[64:65]
	v_readlane_b32 s25, v242, 52
	v_readfirstlane_b32 s0, v10
	v_lshlrev_b64 v[0:1], 1, v[0:1]
	v_add_u32_e32 v8, 0x2000, v10
	v_lshl_add_u64 v[4:5], s[24:25], 0, v[2:3]
	s_mov_b32 m0, s0
	v_lshl_add_u64 v[6:7], s[24:25], 0, v[0:1]
	v_readfirstlane_b32 s0, v8
	v_readlane_b32 s24, v240, 14
	v_add_u32_e32 v8, 0x4000, v10
	global_load_lds_dwordx4 v[4:5], off
	s_mov_b32 m0, s0
	v_readlane_b32 s25, v240, 15
	v_readfirstlane_b32 s0, v8
	v_add_u32_e32 v8, 0x6000, v10
	global_load_lds_dwordx4 v[6:7], off
	v_lshl_add_u64 v[2:3], s[24:25], 0, v[2:3]
	s_mov_b32 m0, s0
	v_readfirstlane_b32 s0, v8
	v_add_u32_e32 v11, 0x8000, v10
	global_load_lds_dwordx4 v[2:3], off
	v_lshl_add_u64 v[0:1], s[24:25], 0, v[0:1]
	s_mov_b32 m0, s0
	v_readfirstlane_b32 s0, v11
	v_add_u32_e32 v11, 0xa000, v10
	global_load_lds_dwordx4 v[0:1], off
	v_lshl_add_u64 v[8:9], v[4:5], 0, 64
	s_mov_b32 m0, s0
	v_readfirstlane_b32 s0, v11
	v_add_u32_e32 v11, 0xc000, v10
	global_load_lds_dwordx4 v[8:9], off
	v_lshl_add_u64 v[8:9], v[6:7], 0, 64
	s_mov_b32 m0, s0
	v_readfirstlane_b32 s0, v11
	v_add_u32_e32 v11, 0xe000, v10
	global_load_lds_dwordx4 v[8:9], off
	v_lshl_add_u64 v[8:9], v[2:3], 0, 64
	s_mov_b32 m0, s0
	v_readfirstlane_b32 s0, v11
	v_add_u32_e32 v11, 0x10000, v10
	global_load_lds_dwordx4 v[8:9], off
	v_lshl_add_u64 v[8:9], v[0:1], 0, 64
	s_mov_b32 m0, s0
	v_readfirstlane_b32 s0, v11
	v_add_u32_e32 v11, 0x12000, v10
	global_load_lds_dwordx4 v[8:9], off
	v_lshl_add_u64 v[8:9], v[4:5], 0, s[34:35]
	s_mov_b32 m0, s0
	v_readfirstlane_b32 s0, v11
	v_add_u32_e32 v11, 0x14000, v10
	global_load_lds_dwordx4 v[8:9], off
	v_lshl_add_u64 v[8:9], v[6:7], 0, s[34:35]
	s_mov_b32 m0, s0
	v_readfirstlane_b32 s0, v11
	v_add_u32_e32 v11, 0x16000, v10
	global_load_lds_dwordx4 v[8:9], off
	v_lshl_add_u64 v[8:9], v[2:3], 0, s[34:35]
	s_mov_b32 m0, s0
	v_readfirstlane_b32 s0, v11
	global_load_lds_dwordx4 v[8:9], off
	v_lshl_add_u64 v[8:9], v[0:1], 0, s[34:35]
	s_mov_b32 m0, s0
	v_lshl_add_u64 v[4:5], v[4:5], 0, s[82:83]
	global_load_lds_dwordx4 v[8:9], off
	v_add_u32_e32 v8, 0x18000, v10
	v_lshl_add_u64 v[2:3], v[2:3], 0, s[82:83]
	v_readfirstlane_b32 s0, v8
	s_mov_b32 m0, s0
	v_lshl_add_u64 v[0:1], v[0:1], 0, s[82:83]
	global_load_lds_dwordx4 v[4:5], off
	v_lshl_add_u64 v[4:5], v[6:7], 0, s[82:83]
	v_add_u32_e32 v6, 0x1a000, v10
	s_mov_b32 s40, 1
	v_readfirstlane_b32 s0, v6
	s_mov_b32 m0, s0
	s_mov_b32 s41, 0
	global_load_lds_dwordx4 v[4:5], off
	v_add_u32_e32 v4, 0x1c000, v10
	s_nop 0
	v_readfirstlane_b32 s0, v4
	s_mov_b32 m0, s0
	s_nop 0
	global_load_lds_dwordx4 v[2:3], off
	v_add_u32_e32 v2, 0x1e000, v10
	s_nop 0
	v_readfirstlane_b32 s0, v2
	s_mov_b32 m0, s0
	v_readlane_b32 s0, v242, 43
	global_load_lds_dwordx4 v[0:1], off
	v_readlane_b32 s1, v242, 44
	s_mov_b32 s30, s0
	v_readlane_b32 s0, v242, 53
	s_mov_b32 s31, s0
	v_readlane_b32 s1, v242, 54
	s_branch .LBB0_1783

.LBB0_1812:
	s_waitcnt vmcnt(0)
	s_waitcnt lgkmcnt(0)
	s_barrier
	s_and_saveexec_b64 s[0:1], s[74:75]
	v_readlane_b32 s22, v243, 15
	v_readlane_b32 s23, v243, 16
	s_cbranch_execz .LBB0_1864
	s_waitcnt vmcnt(0) lgkmcnt(0)
	v_readlane_b32 s4, v240, 63
	v_readlane_b32 s5, v240, 61
	v_readlane_b32 s6, v240, 62
	s_add_u32 s2, s92, 0xb500900
	s_addc_u32 s3, s93, 0
	s_add_i32 s4, s4, 1
	s_nop 1
	v_writelane_b32 v240, s4, 63
	v_mov_b32_e32 v0, s5
	v_lshlrev_b32_e32 v0, 7, v0
	v_lshl_add_u32 v0, s6, 2, v0
	v_add_u32_e32 v0, 0x1400, v0
	v_mov_b32_e32 v1, s4
	global_store_dword v0, v1, s[2:3]
	s_cmp_lg_u32 s6, 0
	s_cbranch_scc1 .Lnc17_f
	buffer_inv sc1
	v_readlane_b32 s7, v240, 60
	s_mov_b32 exec_lo, -1
	s_mov_b32 exec_hi, 0
	v_mbcnt_lo_u32_b32 v2, -1, 0
	s_cmp_lg_u32 s7, 0
	s_cbranch_scc1 .Lnc17_have
	v_lshlrev_b32_e32 v3, 8, v2
	v_add_u32_e32 v3, 0x400, v3
	global_load_dword v4, v3, s[2:3] sc0 sc1
	s_waitcnt vmcnt(0)
	v_readlane_b32 s7, v4, s5
	v_cmp_ne_u32_e32 vcc, 0, v4
	s_nop 3
	s_and_b32 s6, vcc_lo, 0xffff
	v_writelane_b32 v240, s7, 60
	v_writelane_b32 v240, s6, 59
.Lnc17_have:
	v_readlane_b32 s6, v240, 59
	v_lshlrev_b32_e32 v3, 2, v2
	v_lshl_add_u32 v3, s5, 7, v3
	v_add_u32_e32 v3, 0x1400, v3
	v_cmp_le_u32_e32 vcc, s7, v2
	s_nop 1
	v_cndmask_b32_e64 v8, 0, -1, vcc
.Lnc17_p1:
	global_load_dword v4, v3, s[2:3] sc1
	s_waitcnt vmcnt(0)
	v_or_b32_e32 v4, v4, v8
	v_cmp_gt_u32_e32 vcc, s4, v4
	s_cbranch_vccz .Lnc17_ok1
	s_nop 3
	s_branch .Lnc17_p1
.Lnc17_ok1:
	buffer_wbl2 sc1
	s_waitcnt vmcnt(0)
	s_mov_b64 exec, 1
	v_mov_b32_e32 v0, s5
	v_lshlrev_b32_e32 v0, 2, v0
	v_add_u32_e32 v0, 0x3400, v0
	global_store_dword v0, v1, s[2:3] sc0 sc1
	s_mov_b64 exec, 0xffff
	v_lshlrev_b32_e32 v3, 2, v2
	v_add_u32_e32 v3, 0x3400, v3
	v_lshrrev_b32_e64 v9, v2, s6
	v_and_b32_e32 v9, 1, v9
	v_add_u32_e32 v9, -1, v9
.Lnc17_p2:
	global_load_dword v4, v3, s[2:3] sc0 sc1
	s_waitcnt vmcnt(0)
	v_or_b32_e32 v4, v4, v9
	v_cmp_gt_u32_e32 vcc, s4, v4
	s_cbranch_vccz .Lnc17_ok2
	s_sleep 1
	s_branch .Lnc17_p2
.Lnc17_ok2:
	s_mov_b64 exec, 1
	v_mov_b32_e32 v0, s5
	v_lshlrev_b32_e32 v0, 8, v0
	v_add_u32_e32 v0, 0x2400, v0
	global_store_dword v0, v1, s[2:3]
	s_branch .Lnc17_done
.Lnc17_f:
	buffer_inv sc1
	v_mov_b32_e32 v0, s5
	v_lshlrev_b32_e32 v0, 8, v0
	v_add_u32_e32 v0, 0x2400, v0
.Lnc17_p3:
	global_load_dword v3, v0, s[2:3] sc1
	s_waitcnt vmcnt(0)
	v_cmp_gt_u32_e32 vcc, s4, v3
	s_cbranch_vccz .Lnc17_okf
	s_sleep 1
	s_branch .Lnc17_p3
.Lnc17_okf:
.Lnc17_done:
.LBB0_1864:
	s_or_b64 exec, exec, s[0:1]
	s_barrier
	v_readlane_b32 s0, v244, 3
	v_ashrrev_i32_e32 v0, 6, v166
	s_nop 0
	v_add_u32_e32 v16, s0, v0
	s_mov_b32 s0, 0x10000
	v_cmp_gt_i32_e32 vcc, s0, v16
	s_and_saveexec_b64 s[0:1], vcc
	s_cbranch_execz .LBB0_1867
	v_and_b32_e32 v0, 63, v166
	v_readlane_b32 s0, v245, 48
	v_lshlrev_b32_e32 v18, 4, v0
	v_readlane_b32 s12, v245, 60
	v_readlane_b32 s13, v245, 61
	s_nop 4
	global_load_dwordx4 v[0:3], v18, s[12:13]
	global_load_dwordx4 v[4:7], v18, s[12:13] offset:1024
	global_load_dwordx4 v[8:11], v18, s[12:13] offset:2048
	global_load_dwordx4 v[12:15], v18, s[12:13] offset:3072
	v_cmp_lt_i32_e32 vcc, v157, v168
	v_readlane_b32 s4, v245, 52
	v_readlane_b32 s5, v245, 53
	v_cndmask_b32_e32 v17, v155, v157, vcc
	v_cmp_lt_i32_e32 vcc, v169, v168
	v_readlane_b32 s6, v245, 54
	v_readlane_b32 s7, v245, 55
	v_readlane_b32 s14, v245, 62
	v_readlane_b32 s15, v245, 63
	v_lshlrev_b32_e32 v20, 2, v17
	v_cndmask_b32_e32 v17, v155, v169, vcc
	v_mov_b32_e32 v19, 0
	v_lshlrev_b32_e32 v21, 2, v17
	v_lshl_add_u64 v[18:19], s[14:15], 0, v[18:19]
	s_mov_b64 s[4:5], 0
	v_mov_b32_e32 v22, 0x3727c5ac
	s_mov_b32 s6, 0xf800000
	v_mov_b32_e32 v23, 0x260
	s_mov_b32 s7, 0xffff
	v_readlane_b32 s1, v245, 49
	v_readlane_b32 s2, v245, 50
	v_readlane_b32 s3, v245, 51
	v_readlane_b32 s8, v245, 56
	v_readlane_b32 s9, v245, 57
	v_readlane_b32 s10, v245, 58
	v_readlane_b32 s11, v245, 59
